# P2 critical-CU unloading: the 384 sample-pooling wave tasks move from CUs vcu 192..239 (half of which also run a sample-conv unit) to 48 CUs without a sample-conv unit
# speedup vs baseline: 1.0022x; 1.0018x over previous
; __device__ __forceinline__ void p2_pool_sample_task(Frame& F, int sidx) {
;     const int R0 = (256 + sidx / 24) * 32, id = sidx % 24, g = id / 6, q = id % 6, third = q >> 1, half = q & 1;
;     const int r0 = R0 + 16 * half + 4 * (F.lane >> 4), c = g * PGRP + third * 128 + (F.lane & 15) * 8;
;     if (g == 0) pool_task<2, true>(F, r0, c); else if (g == 1) pool_task<4, true>(F, r0, c); else if (g == 2) pool_task<8, true>(F, r0, c); else pool_task<16, true>(F, r0, c);
; __device__ __forceinline__ void p2_mixers(LAS unsigned char* lds, const ConvW& cw) {
;     ...
;     { Frame F = make_frame(lds);
;       for (int sidx = ((F.vcu + F.G - 192) % F.G) * NWAVES + F.wave; sidx < 16 * 24; sidx += F.G * NWAVES) p2_pool_sample_task(F, sidx); }
.LBB0_526:
	s_add_i32 s7, s3, s7
	s_add_i32 s10, s7, 0xffffff40
	s_sub_i32 s7, 0xc0, s7
	s_max_i32 s7, s10, s7
	s_ashr_i32 s11, s10, 31
	s_mul_hi_u32 s10, s7, s44
	s_mul_i32 s10, s10, s29
	s_sub_i32 s7, s7, s10
	s_ashr_i32 s6, s6, 6
	s_sub_i32 s10, s7, s29
	s_cmp_ge_u32 s7, s29
	s_cselect_b32 s7, s10, s7
	s_sub_i32 s10, s7, s29
	s_cmp_ge_u32 s7, s29
	s_cselect_b32 s7, s10, s7
	s_xor_b32 s7, s7, s11
	s_sub_i32 s7, s7, s11
	s_add_i32 s7, s7, 0xc0
	s_and_b32 s7, s7, 0xff
	s_lshr_b32 s10, s7, 2
	s_and_b32 s11, s7, 3
	s_cmp_eq_u32 s11, 2
	s_cselect_b32 s7, s10, 0xff
	s_lshl_b32 s7, s7, 3
	s_add_i32 s29, s7, s6
	s_mov_b64 s[8:9], s[0:1]
	s_cmpk_gt_i32 s29, 0x17f
	s_cbranch_scc1 .LBB0_541
	s_load_dwordx2 s[6:7], s[8:9], 0x28
	s_load_dwordx2 s[10:11], s[8:9], 0xb0
	v_lshrrev_b32_e32 v1, 2, v2
	v_and_b32_e32 v136, 12, v1
	v_lshlrev_b32_e32 v1, 3, v2
	v_and_b32_e32 v137, 0x78, v1
	s_waitcnt lgkmcnt(0)
	s_add_u32 s8, s10, 0x2a00000
	s_addc_u32 s9, s11, 0
	s_add_u32 s10, s10, 0xb800000
	s_addc_u32 s11, s11, 0
	s_mov_b32 s34, 0x16800
	s_mov_b64 s[12:13], 0x1800
	s_mov_b64 s[16:17], 0x3000
	s_movk_i32 s35, 0x3000
	s_mov_b64 s[18:19], 0x4800
	s_movk_i32 s36, 0x4000
	s_mov_b64 s[22:23], 0x6000
	s_movk_i32 s37, 0x6000
	s_mov_b64 s[24:25], 0x7800
	s_movk_i32 s56, 0x7000
	s_mov_b64 s[26:27], 0x9000
	s_mov_b32 s57, 0x9000
	s_mov_b64 s[38:39], 0xa800
	s_mov_b32 s58, 0xa000
	s_mov_b64 s[40:41], 0xc000
	s_mov_b32 s59, 0xc000
	s_mov_b64 s[42:43], 0xd800
	s_mov_b32 s60, 0xd000
	s_mov_b64 s[44:45], 0xf000
	s_mov_b32 s61, 0xf000
	s_mov_b64 s[46:47], 0x10800
	s_mov_b32 s62, 0x10000
	s_mov_b64 s[48:49], 0x12000
	s_mov_b32 s63, 0x12000
	s_mov_b64 s[50:51], 0x13800
	s_mov_b32 s64, 0x13000
	s_mov_b64 s[52:53], 0x15000
	s_mov_b32 s65, 0x15000
	s_movk_i32 s66, 0xc00
	s_mov_b32 s67, 0x3d800000
	s_mov_b32 s68, 0x3e000000
	s_mov_b32 s69, 0x3e800000
	s_branch .LBB0_529
